# split-K partial-sum epilogue also transposed through the per-wave LDS buffer (coalesced 8 rows x 128 B stores)
# speedup vs baseline: 1.0463x; 1.0082x over previous
.LBB0_629:
	s_abs_i32 s19, s50
	s_mul_hi_u32 s20, s19, s47
	s_mul_i32 s21, s20, s26
	s_sub_i32 s19, s19, s21
	s_ashr_i32 s18, s50, 31
	s_add_i32 s21, s20, 1
	s_sub_i32 s35, s19, s26
	s_cmp_ge_u32 s19, s26
	s_cselect_b32 s20, s21, s20
	s_cselect_b32 s19, s35, s19
	s_add_i32 s21, s20, 1
	s_cmp_ge_u32 s19, s26
	s_cselect_b32 s19, s21, s20
	s_xor_b32 s19, s19, s18
	s_sub_i32 s18, s19, s18
	s_ashr_i32 s19, s18, 31
	s_lshl_b64 s[18:19], s[18:19], 21
	v_readlane_b32 s20, v251, 49
	v_readlane_b32 s21, v251, 50
	v_lshrrev_b32_e32 v144, 6, v140
	v_bfe_u32 v145, v142, 5, 2
	v_lshl_add_u32 v144, v144, 2, v145
	s_add_u32 s18, s20, s18
	s_addc_u32 s19, s21, s19
	v_mul_u32_u24_e32 v144, 2304, v144
	v_add_u32_e32 v144, 135424, v144
	v_and_b32_e32 v145, 15, v189
	v_mul_u32_u24_e32 v145, 144, v145
	v_lshrrev_b32_e32 v146, 4, v189
	v_lshl_add_u32 v145, v146, 5, v145
	v_add_u32_e32 v216, v144, v145
	v_lshrrev_b32_e32 v145, 3, v189
	v_and_b32_e32 v146, 7, v189
	v_mul_u32_u24_e32 v217, 144, v145
	v_lshl_add_u32 v217, v146, 4, v217
	v_add_u32_e32 v217, v144, v217
	v_and_b32_e32 v147, 0xfffffff0, v140
	v_add_u32_e32 v147, v147, v145
	v_lshl_add_u32 v147, s51, 8, v147
	v_and_b32_e32 v148, 0x60, v142
	v_lshl_add_u32 v148, s52, 8, v148
	v_lshlrev_b32_e32 v147, 12, v147
	v_lshl_add_u32 v148, v148, 2, v147
	v_lshl_add_u32 v218, v146, 4, v148
	ds_write_b128 v216, v[126:129]
	ds_write_b128 v216, v[122:125] offset:16
	ds_read_b128 v[192:195], v217
	ds_read_b128 v[196:199], v217 offset:1152
	ds_write_b128 v216, v[118:121]
	ds_write_b128 v216, v[114:117] offset:16
	ds_read_b128 v[200:203], v217
	ds_read_b128 v[204:207], v217 offset:1152
	s_waitcnt lgkmcnt(4)
	v_mov_b32_e32 v220, v218
	v_add_u32_e32 v221, 0x8000, v218
	global_store_dwordx4 v220, v[192:195], s[18:19]
	global_store_dwordx4 v221, v[196:199], s[18:19]
	ds_write_b128 v216, v[108:111]
	ds_write_b128 v216, v[104:107] offset:16
	ds_read_b128 v[208:211], v217
	ds_read_b128 v[212:215], v217 offset:1152
	s_waitcnt lgkmcnt(4)
	v_add_u32_e32 v222, 0x200, v218
	v_add_u32_e32 v223, 0x8200, v218
	global_store_dwordx4 v222, v[200:203], s[18:19]
	global_store_dwordx4 v223, v[204:207], s[18:19]
	ds_write_b128 v216, v[100:103]
	ds_write_b128 v216, v[96:99] offset:16
	ds_read_b128 v[192:195], v217
	ds_read_b128 v[196:199], v217 offset:1152
	s_waitcnt lgkmcnt(4)
	v_add_u32_e32 v224, 0x10000, v218
	v_add_u32_e32 v225, 0x18000, v218
	global_store_dwordx4 v224, v[208:211], s[18:19]
	global_store_dwordx4 v225, v[212:215], s[18:19]
	ds_write_b128 v216, v[92:95]
	ds_write_b128 v216, v[88:91] offset:16
	ds_read_b128 v[200:203], v217
	ds_read_b128 v[204:207], v217 offset:1152
	s_waitcnt lgkmcnt(4)
	v_add_u32_e32 v226, 0x10200, v218
	v_add_u32_e32 v227, 0x18200, v218
	global_store_dwordx4 v226, v[192:195], s[18:19]
	global_store_dwordx4 v227, v[196:199], s[18:19]
	ds_write_b128 v216, v[84:87]
	ds_write_b128 v216, v[80:83] offset:16
	ds_read_b128 v[208:211], v217
	ds_read_b128 v[212:215], v217 offset:1152
	s_waitcnt lgkmcnt(4)
	v_add_u32_e32 v220, 0x20000, v218
	v_add_u32_e32 v221, 0x28000, v218
	global_store_dwordx4 v220, v[200:203], s[18:19]
	global_store_dwordx4 v221, v[204:207], s[18:19]
	ds_write_b128 v216, v[76:79]
	ds_write_b128 v216, v[72:75] offset:16
	ds_read_b128 v[192:195], v217
	ds_read_b128 v[196:199], v217 offset:1152
	s_waitcnt lgkmcnt(4)
	v_add_u32_e32 v222, 0x20200, v218
	v_add_u32_e32 v223, 0x28200, v218
	global_store_dwordx4 v222, v[208:211], s[18:19]
	global_store_dwordx4 v223, v[212:215], s[18:19]
	ds_write_b128 v216, v[68:71]
	ds_write_b128 v216, v[64:67] offset:16
	ds_read_b128 v[200:203], v217
	ds_read_b128 v[204:207], v217 offset:1152
	s_waitcnt lgkmcnt(4)
	v_add_u32_e32 v224, 0x30000, v218
	v_add_u32_e32 v225, 0x38000, v218
	global_store_dwordx4 v224, v[192:195], s[18:19]
	global_store_dwordx4 v225, v[196:199], s[18:19]
	ds_write_b128 v216, v[60:63]
	ds_write_b128 v216, v[56:59] offset:16
	ds_read_b128 v[208:211], v217
	ds_read_b128 v[212:215], v217 offset:1152
	s_waitcnt lgkmcnt(4)
	v_add_u32_e32 v226, 0x30200, v218
	v_add_u32_e32 v227, 0x38200, v218
	global_store_dwordx4 v226, v[200:203], s[18:19]
	global_store_dwordx4 v227, v[204:207], s[18:19]
	ds_write_b128 v216, v[52:55]
	ds_write_b128 v216, v[48:51] offset:16
	ds_read_b128 v[192:195], v217
	ds_read_b128 v[196:199], v217 offset:1152
	s_waitcnt lgkmcnt(4)
	v_add_u32_e32 v220, 0x80000, v218
	v_add_u32_e32 v221, 0x88000, v218
	global_store_dwordx4 v220, v[208:211], s[18:19]
	global_store_dwordx4 v221, v[212:215], s[18:19]
	ds_write_b128 v216, v[44:47]
	ds_write_b128 v216, v[40:43] offset:16
	ds_read_b128 v[200:203], v217
	ds_read_b128 v[204:207], v217 offset:1152
	s_waitcnt lgkmcnt(4)
	v_add_u32_e32 v222, 0x80200, v218
	v_add_u32_e32 v223, 0x88200, v218
	global_store_dwordx4 v222, v[192:195], s[18:19]
	global_store_dwordx4 v223, v[196:199], s[18:19]
	ds_write_b128 v216, v[36:39]
	ds_write_b128 v216, v[32:35] offset:16
	ds_read_b128 v[208:211], v217
	ds_read_b128 v[212:215], v217 offset:1152
	s_waitcnt lgkmcnt(4)
	v_add_u32_e32 v224, 0x90000, v218
	v_add_u32_e32 v225, 0x98000, v218
	global_store_dwordx4 v224, v[200:203], s[18:19]
	global_store_dwordx4 v225, v[204:207], s[18:19]
	ds_write_b128 v216, v[28:31]
	ds_write_b128 v216, v[24:27] offset:16
	ds_read_b128 v[192:195], v217
	ds_read_b128 v[196:199], v217 offset:1152
	s_waitcnt lgkmcnt(4)
	v_add_u32_e32 v226, 0x90200, v218
	v_add_u32_e32 v227, 0x98200, v218
	global_store_dwordx4 v226, v[208:211], s[18:19]
	global_store_dwordx4 v227, v[212:215], s[18:19]
	ds_write_b128 v216, v[20:23]
	ds_write_b128 v216, v[16:19] offset:16
	ds_read_b128 v[200:203], v217
	ds_read_b128 v[204:207], v217 offset:1152
	s_waitcnt lgkmcnt(4)
	v_add_u32_e32 v220, 0xa0000, v218
	v_add_u32_e32 v221, 0xa8000, v218
	global_store_dwordx4 v220, v[192:195], s[18:19]
	global_store_dwordx4 v221, v[196:199], s[18:19]
	ds_write_b128 v216, v[12:15]
	ds_write_b128 v216, v[8:11] offset:16
	ds_read_b128 v[208:211], v217
	ds_read_b128 v[212:215], v217 offset:1152
	s_waitcnt lgkmcnt(4)
	v_add_u32_e32 v222, 0xa0200, v218
	v_add_u32_e32 v223, 0xa8200, v218
	global_store_dwordx4 v222, v[200:203], s[18:19]
	global_store_dwordx4 v223, v[204:207], s[18:19]
	ds_write_b128 v216, v[4:7]
	ds_write_b128 v216, v[0:3] offset:16
	ds_read_b128 v[192:195], v217
	ds_read_b128 v[196:199], v217 offset:1152
	s_waitcnt lgkmcnt(4)
	v_add_u32_e32 v224, 0xb0000, v218
	v_add_u32_e32 v225, 0xb8000, v218
	global_store_dwordx4 v224, v[208:211], s[18:19]
	global_store_dwordx4 v225, v[212:215], s[18:19]
	s_waitcnt lgkmcnt(0)
	v_add_u32_e32 v226, 0xb0200, v218
	v_add_u32_e32 v227, 0xb8200, v218
	global_store_dwordx4 v226, v[192:195], s[18:19]
	global_store_dwordx4 v227, v[196:199], s[18:19]
	s_mov_b64 s[18:19], -1
	s_and_b64 vcc, exec, s[36:37]
	s_cbranch_vccnz .LBB0_617
	s_andn2_b64 vcc, exec, s[0:1]
	s_cbranch_vccnz .LBB0_616
	s_barrier
	s_branch .LBB0_616
